# pb4: waves 4-7 do weight copies before sample scans
# baseline (speedup 1.0000x reference)
.LBB0_1147:
	s_lshl_b32 s88, s3, 3
	s_addk_i32 s88, 0xff00
	s_mov_b32 s100, 0
	s_bitcmp1_b32 s87, 10
	s_cbranch_scc0 .Lmy_samples_first
	s_mov_b32 s100, 1
	s_mov_b32 s101, s3
	s_branch .LBB0_1195
.Lmy_samples_first:
	s_cmpk_gt_i32 s87, 0x1cff
	s_cbranch_scc1 .LBB0_1195
	v_readlane_b32 s0, v255, 40
	v_readlane_b32 s1, v255, 41
	s_lshl_b64 s[14:15], s[0:1], 18
	v_readlane_b32 s0, v255, 52
	v_readlane_b32 s1, v255, 53
	s_add_u32 s0, s12, s0
	s_addc_u32 s1, s13, s1
	s_add_u32 s80, s0, 0x27800000
	s_addc_u32 s81, s1, 0
	s_add_u32 s0, s12, s14
	s_addc_u32 s1, s13, s15
	s_add_u32 s0, s0, 0x27810000
	s_addc_u32 s1, s1, 0
	s_add_u32 s89, s12, 0x422e2000
	s_addc_u32 s90, s13, 0
	s_add_u32 s20, s12, 0x1ec00000
	v_writelane_b32 v255, s0, 50
	s_addc_u32 s21, s13, 0
	s_mov_b32 s27, s39
	v_writelane_b32 v255, s1, 51
	s_add_u32 s0, s12, 0x2c652000
	v_writelane_b32 v255, s0, 54
	s_addc_u32 s0, s13, 0
	v_writelane_b32 v255, s0, 52
	s_add_u32 s0, s10, 0x117dc000
	v_writelane_b32 v255, s0, 58
	s_addc_u32 s0, s11, 0
	s_add_u32 s22, s12, 0x292f2000
	s_addc_u32 s23, s13, 0
	s_add_u32 s24, s12, 0x281d2000
	s_addc_u32 s25, s13, 0
	v_writelane_b32 v255, s0, 59
	s_add_u32 s0, s12, 0x2b532000
	v_writelane_b32 v255, s0, 56
	s_addc_u32 s0, s13, 0
	s_add_u32 s29, s12, 0x1ec01a00
	v_writelane_b32 v255, s0, 44
	s_addc_u32 s0, s13, 0
	s_add_u32 s94, s10, 0x95dc000
	s_addc_u32 s16, s11, 0
	s_and_b32 s26, s87, 7
	v_writelane_b32 v255, s0, 46
	s_lshl_b32 s0, s26, 6
	s_or_b32 s30, s34, s0
	s_lshl_b32 s0, s26, 8
	s_add_u32 s0, s12, s0
	s_addc_u32 s1, s13, 0
	s_add_u32 s78, s0, 0x3ab02000
	s_addc_u32 s79, s1, 0
	s_lshl_b32 s0, s26, 7
	s_add_u32 s0, s12, s0
	s_addc_u32 s1, s13, 0
	s_add_u32 s92, s0, 0x25500000
	s_addc_u32 s93, s1, 0
	s_add_i32 s17, s86, 0x3000
	s_add_u32 s0, s12, 0x24cc2400
	v_writelane_b32 v255, s0, 60
	s_addc_u32 s0, s13, 0
	v_writelane_b32 v255, s0, 61
	v_readlane_b32 s0, v254, 36
	s_add_i32 s18, s0, s2
	s_add_u32 s0, s12, 0x2ac22000
	v_writelane_b32 v255, s0, 62
	s_addc_u32 s0, s13, 0
	v_writelane_b32 v255, s0, 63
	v_readlane_b32 s0, v254, 37
	s_mov_b32 s31, s35
	s_add_i32 s19, s0, s2
	v_mov_b32_e32 v64, v224
	s_mov_b32 s76, s95
	s_branch .LBB0_1150

.LBB0_1197:
	s_cmp_eq_u32 s100, 2
	s_cbranch_scc1 .LBB0_1314
	v_readlane_b32 s0, v255, 40
	v_readlane_b32 s1, v255, 41
	s_cmp_lg_u32 s0, 3
	s_cselect_b64 s[0:1], -1, 0
	s_cmpk_lt_i32 s87, 0x3180
	s_cselect_b64 s[2:3], -1, 0
	s_and_b64 s[0:1], s[0:1], s[2:3]
	s_andn2_b64 vcc, exec, s[0:1]
	s_cbranch_vccnz .LBB0_1314
	v_readlane_b32 s70, v255, 42
	v_readlane_b32 s52, v253, 14
	v_readlane_b32 s71, v255, 43
	v_readlane_b32 s60, v253, 22
	v_readlane_b32 s61, v253, 23
	s_mov_b32 s71, s39
	v_readlane_b32 s62, v253, 24
	v_readlane_b32 s63, v253, 25
	v_readlane_b32 s64, v253, 26
	v_readlane_b32 s65, v253, 27
	v_readlane_b32 s66, v253, 28
	v_readlane_b32 s67, v253, 29
	s_mov_b64 s[24:25], s[60:61]
	s_lshl_b64 s[0:1], s[70:71], 13
	s_lshl_b64 s[2:3], s[70:71], 20
	s_mov_b64 s[30:31], s[66:67]
	s_mov_b64 s[26:27], s[62:63]
	s_mov_b64 s[28:29], s[64:65]
	s_add_u32 s2, s30, s2
	s_addc_u32 s3, s31, s3
	v_readlane_b32 s24, v253, 6
	s_mul_i32 s21, s70, 0x2b00000
	v_readlane_b32 s53, v253, 15
	v_readlane_b32 s54, v253, 16
	v_readlane_b32 s55, v253, 17
	v_readlane_b32 s56, v253, 18
	v_readlane_b32 s57, v253, 19
	v_readlane_b32 s58, v253, 20
	v_readlane_b32 s59, v253, 21
	v_readlane_b32 s28, v253, 10
	s_mul_hi_u32 s20, s70, 0x2b00000
	v_readlane_b32 s29, v253, 11
	s_add_u32 s4, s28, s21
	v_readlane_b32 s52, v255, 24
	s_mul_i32 s6, s70, 0x5600000
	s_addc_u32 s5, s29, s20
	v_readlane_b32 s66, v255, 38
	s_mul_hi_u32 s7, s70, 0x5600000
	v_readlane_b32 s67, v255, 39
	s_add_u32 s6, s66, s6
	v_readlane_b32 s64, v255, 36
	s_addc_u32 s7, s67, s7
	v_readlane_b32 s53, v255, 25
	v_readlane_b32 s54, v255, 26
	v_readlane_b32 s55, v255, 27
	v_readlane_b32 s56, v255, 28
	v_readlane_b32 s57, v255, 29
	v_readlane_b32 s58, v255, 30
	v_readlane_b32 s59, v255, 31
	v_readlane_b32 s60, v255, 32
	v_readlane_b32 s61, v255, 33
	v_readlane_b32 s62, v255, 34
	v_readlane_b32 s63, v255, 35
	v_readlane_b32 s65, v255, 37
	s_add_u32 s8, s64, s0
	s_addc_u32 s9, s65, s1
	v_readlane_b32 s52, v254, 50
	s_lshl_b64 s[14:15], s[70:71], 24
	v_readlane_b32 s60, v254, 58
	v_readlane_b32 s61, v254, 59
	s_add_u32 s14, s60, s14
	s_mul_i32 s16, s70, 0x2e20000
	v_readlane_b32 s58, v254, 56
	s_addc_u32 s15, s61, s15
	s_mul_hi_u32 s17, s70, 0x2e20000
	v_readlane_b32 s59, v254, 57
	s_add_u32 s16, s58, s16
	v_readlane_b32 s56, v254, 54
	s_addc_u32 s17, s59, s17
	v_readlane_b32 s57, v254, 55
	s_add_u32 s18, s56, s0
	s_addc_u32 s19, s57, s1
	s_lshl_b64 s[0:1], s[70:71], 19
	v_lshlrev_b32_e32 v0, 3, v64
	s_add_u32 s0, s12, s0
	v_and_b32_e32 v6, 56, v0
	s_addc_u32 s1, s13, s1
	v_lshlrev_b32_e32 v96, 1, v6
	v_lshl_add_u64 v[0:1], s[0:1], 0, v[96:97]
	s_mul_i32 s0, s70, 0x1580000
	s_mul_hi_u32 s22, s70, 0x1580000
	s_add_u32 s0, s12, s0
	s_addc_u32 s1, s13, s22
	v_lshl_add_u64 v[2:3], s[0:1], 0, v[96:97]
	s_add_u32 s0, s12, s21
	s_addc_u32 s1, s13, s20
	s_mov_b32 s20, s70
	v_readlane_b32 s66, v255, 0
	v_readlane_b32 s67, v255, 1
	v_writelane_b32 v255, s20, 42
	v_lshl_add_u64 v[4:5], s[0:1], 0, v[96:97]
	s_lshl_b64 s[0:1], s[70:71], 23
	v_writelane_b32 v255, s21, 43
	v_ashrrev_i32_e32 v66, 4, v64
	s_movk_i32 s20, 0x84
	s_add_u32 s0, s12, s0
	v_mul_lo_u32 v82, v66, s20
	v_ashrrev_i32_e32 v83, 3, v64
	s_mov_b64 s[20:21], 0x3a902000
	s_addc_u32 s1, s13, s1
	v_lshlrev_b32_e32 v7, 2, v64
	v_mul_u32_u24_e32 v6, 0x84, v6
	v_lshl_add_u64 v[64:65], v[0:1], 0, s[20:21]
	v_lshlrev_b32_e32 v0, 1, v83
	s_mul_i32 s23, s70, 0x1800000
	v_add3_u32 v84, s86, v6, v0
	v_lshl_add_u64 v[0:1], s[0:1], 0, v[96:97]
	s_mov_b64 s[0:1], 0x6100000
	s_mul_hi_u32 s22, s70, 0x1800000
	v_lshl_add_u64 v[72:73], v[0:1], 0, s[0:1]
	s_add_u32 s0, s12, s23
	s_mov_b64 s[20:21], 0x12d00000
	s_addc_u32 s1, s13, s22
	v_readlane_b32 s25, v253, 7
	v_readlane_b32 s26, v253, 8
	v_readlane_b32 s27, v253, 9
	v_readlane_b32 s53, v254, 51
	v_and_b32_e32 v80, 60, v7
	v_lshl_add_u64 v[68:69], v[2:3], 0, s[20:21]
	s_mov_b64 s[20:21], 0x8100000
	v_lshl_add_u64 v[0:1], s[0:1], 0, v[96:97]
	s_mov_b64 s[0:1], 0x100000
	s_movk_i32 s53, 0x6000
	s_movk_i32 s52, 0x4000
	v_lshl_add_u32 v81, v80, 1, s86
	v_add_u32_e32 v85, 8, v83
	v_add_u32_e32 v86, 16, v83
	v_add_u32_e32 v87, 24, v83
	v_add_u32_e32 v88, 32, v83
	v_add_u32_e32 v89, 40, v83
	v_add_u32_e32 v90, 48, v83
	v_add_u32_e32 v91, 56, v83
	v_add_u32_e32 v92, 0x210, v82
	v_lshl_add_u64 v[70:71], v[4:5], 0, s[20:21]
	v_lshl_add_u64 v[74:75], v[0:1], 0, s[0:1]
	v_ashrrev_i32_e32 v67, 31, v66
	s_lshl_b32 s22, s95, 6
	s_lshl_b32 s23, s88, 6
	s_lshl_b32 s24, s95, 3
	s_lshl_b32 s25, s88, 3
	s_lshl_b32 s26, s95, 1
	s_lshl_b32 s27, s88, 1
	v_readlane_b32 s30, v253, 12
	v_readlane_b32 s31, v253, 13
	v_readlane_b32 s54, v254, 52
	v_readlane_b32 s55, v254, 53
	v_readlane_b32 s62, v254, 60
	v_readlane_b32 s63, v254, 61
	v_readlane_b32 s64, v254, 62
	v_readlane_b32 s65, v254, 63
	s_branch .LBB0_1202

.Lmy_redo_samples:
	s_mov_b32 s100, 2
	s_mov_b32 s3, s101
	v_readlane_b32 s2, v255, 4
	s_add_i32 s95, s87, 0xffffff00
	s_movk_i32 s52, 0x4000
	s_movk_i32 s53, 0x6000
	s_mul_i32 s2, s3, s2
	s_branch .Lmy_samples_first
.LBB0_1314:
	s_cmp_eq_u32 s100, 1
	s_cbranch_scc1 .Lmy_redo_samples
	s_mov_b64 s[0:1], 0
	s_mov_b32 s95, 0x7f800000

	.amdhsa_kernel _Z3fwd4Args
		.amdhsa_group_segment_fixed_size 0
		.amdhsa_private_segment_fixed_size 0
		.amdhsa_kernarg_size 632
		.amdhsa_user_sgpr_count 2
		.amdhsa_user_sgpr_dispatch_ptr 0
		.amdhsa_user_sgpr_queue_ptr 0
		.amdhsa_user_sgpr_kernarg_segment_ptr 1
		.amdhsa_user_sgpr_dispatch_id 0
		.amdhsa_user_sgpr_kernarg_preload_length 0
		.amdhsa_user_sgpr_kernarg_preload_offset 0
		.amdhsa_user_sgpr_private_segment_size 0
		.amdhsa_uses_dynamic_stack 0
		.amdhsa_enable_private_segment 0
		.amdhsa_system_sgpr_workgroup_id_x 1
		.amdhsa_system_sgpr_workgroup_id_y 0
		.amdhsa_system_sgpr_workgroup_id_z 0
		.amdhsa_system_sgpr_workgroup_info 0
		.amdhsa_system_vgpr_workitem_id 0
		.amdhsa_next_free_vgpr 256
		.amdhsa_next_free_sgpr 102
		.amdhsa_accum_offset 256
		.amdhsa_reserve_vcc 1
		.amdhsa_float_round_mode_32 0
		.amdhsa_float_round_mode_16_64 0
		.amdhsa_float_denorm_mode_32 3
		.amdhsa_float_denorm_mode_16_64 3
		.amdhsa_dx10_clamp 1
		.amdhsa_ieee_mode 1
		.amdhsa_fp16_overflow 0
		.amdhsa_tg_split 0
		.amdhsa_exception_fp_ieee_invalid_op 0
		.amdhsa_exception_fp_denorm_src 0
		.amdhsa_exception_fp_ieee_div_zero 0
		.amdhsa_exception_fp_ieee_overflow 0
		.amdhsa_exception_fp_ieee_underflow 0
		.amdhsa_exception_fp_ieee_inexact 0
		.amdhsa_exception_int_div_zero 0
	.end_amdhsa_kernel

amdhsa.kernels:
  - .agpr_count:     0
    .args:
      - .offset:         0
        .size:           376
        .value_kind:     by_value
      - .offset:         376
        .size:           4
        .value_kind:     hidden_block_count_x
      - .offset:         380
        .size:           4
        .value_kind:     hidden_block_count_y
      - .offset:         384
        .size:           4
        .value_kind:     hidden_block_count_z
      - .offset:         388
        .size:           2
        .value_kind:     hidden_group_size_x
      - .offset:         390
        .size:           2
        .value_kind:     hidden_group_size_y
      - .offset:         392
        .size:           2
        .value_kind:     hidden_group_size_z
      - .offset:         394
        .size:           2
        .value_kind:     hidden_remainder_x
      - .offset:         396
        .size:           2
        .value_kind:     hidden_remainder_y
      - .offset:         398
        .size:           2
        .value_kind:     hidden_remainder_z
      - .offset:         416
        .size:           8
        .value_kind:     hidden_global_offset_x
      - .offset:         424
        .size:           8
        .value_kind:     hidden_global_offset_y
      - .offset:         432
        .size:           8
        .value_kind:     hidden_global_offset_z
      - .offset:         440
        .size:           2
        .value_kind:     hidden_grid_dims
      - .offset:         496
        .size:           4
        .value_kind:     hidden_dynamic_lds_size
    .group_segment_fixed_size: 0
    .kernarg_segment_align: 8
    .kernarg_segment_size: 632
    .language:       OpenCL C
    .language_version:
      - 2
      - 0
    .max_flat_workgroup_size: 512
    .name:           _Z3fwd4Args
    .private_segment_fixed_size: 0
    .sgpr_count:     108
    .sgpr_spill_count: 251
    .symbol:         _Z3fwd4Args.kd
    .uniform_work_group_size: 1
    .uses_dynamic_stack: false
    .vgpr_count:     256
    .vgpr_spill_count: 0
    .wavefront_size: 64
